# hand-written lean GEMM epilogue for plain/colscale/relu2 outputs (no per-block address recompute, no drains)
# speedup vs baseline: 1.0074x; 1.0074x over previous
; __device__ __forceinline__ unsigned cvt_pk_bf16(float lo, float hi) { unsigned r; asm volatile("v_cvt_pk_bf16_f32 %0, %1, %2" : "=v"(r) : "v"(lo), "v"(hi)); return r; }
; __device__ __forceinline__ void epi_store(const f32x4 (&acc)[2][2][4][2], const Unit& u, int wr, int wc, int fr, int fq, const EpiP& e) {
;     const int row0 = u.pm * BM + wr * 64 + fr;
;     if (e.mode < 2) {
;         const int col0 = u.pn * BM + wc * 32 + 8 * fq;
; #pragma unroll
;         for (int bj = 0; bj < 2; ++bj) {
;             const int c = col0 + bj * HALF;
;             f32x4 cs0 = {1.f, 1.f, 1.f, 1.f}, cs1 = {1.f, 1.f, 1.f, 1.f};
;             if (e.mode == 0 && e.colscale) { cs0 = *(const f32x4*)(e.colscale + c); cs1 = *(const f32x4*)(e.colscale + c + 4); }
; #pragma unroll
;             for (int ai = 0; ai < 2; ++ai)
; #pragma unroll
;                 for (int m = 0; m < 4; ++m) {
;                     const int row = row0 + ai * HALF + m * 16;
;                     f32x4 v0 = acc[ai][bj][m][0], v1 = acc[ai][bj][m][1];
;                     if (e.mode == 1) {
; #pragma unroll
;                         for (int j = 0; j < 4; ++j) { const float a = fmaxf(v0[j], 0.f), b = fmaxf(v1[j], 0.f); v0[j] = a * a; v1[j] = b * b; }
;                     } else { v0 *= cs0; v1 *= cs1; }
;                     bf16_t* rowp = (u.ks < 0 ? e.O + (size_t)row * e.ldo : e.Opart + ((size_t)u.ks * MCTX + (row - MLAT)) * 1024) + c;
;                     if (e.mode == 1)
;                         rowp = (bf16_t*)((char*)e.O + ((size_t)(u.pm * 64 + u.pn * 4 + bj * 2 + (wc >> 1))) * 32768 + ai * 16384 + (((wr * 4 + m) * 2 + (wc & 1)) * 1024) + (fr * 4 + fq) * 16);
;                     u32x4 w; w.x = cvt_pk_bf16(v0[0], v0[1]); w.y = cvt_pk_bf16(v0[2], v0[3]); w.z = cvt_pk_bf16(v1[0], v1[1]); w.w = cvt_pk_bf16(v1[2], v1[3]);
;                     *(u32x4*)rowp = w;
;                 }
;         }
;         return;
;     }
.LBB0_440:
	s_and_b64 vcc, exec, s[16:17]
	s_cbranch_vccz .LBB0_439
	v_and_b32_e32 v217, 15, v159
	v_lshrrev_b32_e32 v218, 8, v159
	v_bfe_u32 v219, v159, 4, 2
	s_and_b64 vcc, exec, s[10:11]
	s_cbranch_vccnz .Lep1_setup
	s_cmp_gt_i32 s42, -1
	s_cbranch_scc1 .Lep0_part
	s_mov_b32 s18, s70
	s_mul_i32 s16, s87, s70
	s_lshl_b32 s16, s16, 9
	s_lshl_b32 s17, s85, 9
	s_add_u32 s16, s16, s17
	s_add_u32 s100, s74, s16
	s_addc_u32 s101, s75, 0
	s_branch .Lep0_common
.Lep0_part:
	s_movk_i32 s18, 0x400
	s_lshl_b32 s16, s42, 12
	s_lshl_b32 s17, s87, 8
	s_add_i32 s16, s16, s17
	s_sub_i32 s16, s16, 0x8000
	s_lshl_b32 s16, s16, 11
	s_lshl_b32 s17, s85, 9
	s_add_u32 s16, s16, s17
	v_readlane_b32 s20, v253, 8
	v_readlane_b32 s21, v253, 9
	s_add_u32 s100, s20, s16
	s_addc_u32 s101, s21, 0
.Lep0_common:
	v_lshl_or_b32 v217, v218, 6, v217
	v_bfe_u32 v218, v159, 6, 2
	v_lshlrev_b32_e32 v218, 5, v218
	v_lshl_or_b32 v218, v219, 3, v218
	v_mul_lo_u32 v217, v217, s18
	v_add_lshl_u32 v216, v217, v218, 1
	s_lshl_b32 s17, s18, 5
	v_readlane_b32 s20, v255, 26
	v_readlane_b32 s21, v255, 27
	s_and_b64 vcc, exec, s[20:21]
	s_cbranch_vccnz .Lep0_cs
	s_mov_b64 s[98:99], s[100:101]
	v_cvt_pk_bf16_f32 v244, v128, v129
	v_cvt_pk_bf16_f32 v245, v130, v131
	v_cvt_pk_bf16_f32 v246, v124, v125
	v_cvt_pk_bf16_f32 v247, v126, v127
	global_store_dwordx4 v216, v[244:247], s[98:99]
	s_mul_i32 s16, s17, 1
	s_add_u32 s98, s100, s16
	s_addc_u32 s99, s101, 0
	v_cvt_pk_bf16_f32 v248, v120, v121
	v_cvt_pk_bf16_f32 v249, v122, v123
	v_cvt_pk_bf16_f32 v250, v116, v117
	v_cvt_pk_bf16_f32 v251, v118, v119
	global_store_dwordx4 v216, v[248:251], s[98:99]
	s_mul_i32 s16, s17, 2
	s_add_u32 s98, s100, s16
	s_addc_u32 s99, s101, 0
	v_cvt_pk_bf16_f32 v204, v112, v113
	v_cvt_pk_bf16_f32 v205, v114, v115
	v_cvt_pk_bf16_f32 v206, v108, v109
	v_cvt_pk_bf16_f32 v207, v110, v111
	global_store_dwordx4 v216, v[204:207], s[98:99]
	s_mul_i32 s16, s17, 3
	s_add_u32 s98, s100, s16
	s_addc_u32 s99, s101, 0
	v_cvt_pk_bf16_f32 v132, v104, v105
	v_cvt_pk_bf16_f32 v133, v106, v107
	v_cvt_pk_bf16_f32 v134, v100, v101
	v_cvt_pk_bf16_f32 v135, v102, v103
	global_store_dwordx4 v216, v[132:135], s[98:99]
	s_mul_i32 s16, s17, 8
	s_add_u32 s98, s100, s16
	s_addc_u32 s99, s101, 0
	v_cvt_pk_bf16_f32 v136, v60, v61
	v_cvt_pk_bf16_f32 v137, v62, v63
	v_cvt_pk_bf16_f32 v138, v56, v57
	v_cvt_pk_bf16_f32 v139, v58, v59
	global_store_dwordx4 v216, v[136:139], s[98:99]
	s_mul_i32 s16, s17, 9
	s_add_u32 s98, s100, s16
	s_addc_u32 s99, s101, 0
	v_cvt_pk_bf16_f32 v160, v52, v53
	v_cvt_pk_bf16_f32 v161, v54, v55
	v_cvt_pk_bf16_f32 v162, v48, v49
	v_cvt_pk_bf16_f32 v163, v50, v51
	global_store_dwordx4 v216, v[160:163], s[98:99]
	s_mul_i32 s16, s17, 10
	s_add_u32 s98, s100, s16
	s_addc_u32 s99, s101, 0
	v_cvt_pk_bf16_f32 v164, v44, v45
	v_cvt_pk_bf16_f32 v165, v46, v47
	v_cvt_pk_bf16_f32 v166, v40, v41
	v_cvt_pk_bf16_f32 v167, v42, v43
	global_store_dwordx4 v216, v[164:167], s[98:99]
	s_mul_i32 s16, s17, 11
	s_add_u32 s98, s100, s16
	s_addc_u32 s99, s101, 0
	v_cvt_pk_bf16_f32 v168, v36, v37
	v_cvt_pk_bf16_f32 v169, v38, v39
	v_cvt_pk_bf16_f32 v170, v32, v33
	v_cvt_pk_bf16_f32 v171, v34, v35
	global_store_dwordx4 v216, v[168:171], s[98:99]
	s_mov_b64 s[98:99], s[100:101]
	v_cvt_pk_bf16_f32 v244, v92, v93
	v_cvt_pk_bf16_f32 v245, v94, v95
	v_cvt_pk_bf16_f32 v246, v88, v89
	v_cvt_pk_bf16_f32 v247, v90, v91
	global_store_dwordx4 v216, v[244:247], s[98:99] offset:256
	s_mul_i32 s16, s17, 1
	s_add_u32 s98, s100, s16
	s_addc_u32 s99, s101, 0
	v_cvt_pk_bf16_f32 v248, v84, v85
	v_cvt_pk_bf16_f32 v249, v86, v87
	v_cvt_pk_bf16_f32 v250, v80, v81
	v_cvt_pk_bf16_f32 v251, v82, v83
	global_store_dwordx4 v216, v[248:251], s[98:99] offset:256
	s_mul_i32 s16, s17, 2
	s_add_u32 s98, s100, s16
	s_addc_u32 s99, s101, 0
	v_cvt_pk_bf16_f32 v204, v76, v77
	v_cvt_pk_bf16_f32 v205, v78, v79
	v_cvt_pk_bf16_f32 v206, v72, v73
	v_cvt_pk_bf16_f32 v207, v74, v75
	global_store_dwordx4 v216, v[204:207], s[98:99] offset:256
	s_mul_i32 s16, s17, 3
	s_add_u32 s98, s100, s16
	s_addc_u32 s99, s101, 0
	v_cvt_pk_bf16_f32 v132, v68, v69
	v_cvt_pk_bf16_f32 v133, v70, v71
	v_cvt_pk_bf16_f32 v134, v64, v65
	v_cvt_pk_bf16_f32 v135, v66, v67
	global_store_dwordx4 v216, v[132:135], s[98:99] offset:256
	s_mul_i32 s16, s17, 8
	s_add_u32 s98, s100, s16
	s_addc_u32 s99, s101, 0
	v_cvt_pk_bf16_f32 v136, v28, v29
	v_cvt_pk_bf16_f32 v137, v30, v31
	v_cvt_pk_bf16_f32 v138, v24, v25
	v_cvt_pk_bf16_f32 v139, v26, v27
	global_store_dwordx4 v216, v[136:139], s[98:99] offset:256
	s_mul_i32 s16, s17, 9
	s_add_u32 s98, s100, s16
	s_addc_u32 s99, s101, 0
	v_cvt_pk_bf16_f32 v160, v20, v21
	v_cvt_pk_bf16_f32 v161, v22, v23
	v_cvt_pk_bf16_f32 v162, v16, v17
	v_cvt_pk_bf16_f32 v163, v18, v19
	global_store_dwordx4 v216, v[160:163], s[98:99] offset:256
	s_mul_i32 s16, s17, 10
	s_add_u32 s98, s100, s16
	s_addc_u32 s99, s101, 0
	v_cvt_pk_bf16_f32 v164, v12, v13
	v_cvt_pk_bf16_f32 v165, v14, v15
	v_cvt_pk_bf16_f32 v166, v8, v9
	v_cvt_pk_bf16_f32 v167, v10, v11
	global_store_dwordx4 v216, v[164:167], s[98:99] offset:256
	s_mul_i32 s16, s17, 11
	s_add_u32 s98, s100, s16
	s_addc_u32 s99, s101, 0
	v_cvt_pk_bf16_f32 v168, v4, v5
	v_cvt_pk_bf16_f32 v169, v6, v7
	v_cvt_pk_bf16_f32 v170, v0, v1
	v_cvt_pk_bf16_f32 v171, v2, v3
	global_store_dwordx4 v216, v[168:171], s[98:99] offset:256
	s_branch .Lep_done
; __device__ __forceinline__ unsigned cvt_pk_bf16(float lo, float hi) { unsigned r; asm volatile("v_cvt_pk_bf16_f32 %0, %1, %2" : "=v"(r) : "v"(lo), "v"(hi)); return r; }
; __device__ __forceinline__ void epi_store(const f32x4 (&acc)[2][2][4][2], const Unit& u, int wr, int wc, int fr, int fq, const EpiP& e) {
;     ...
;         const int col0 = u.pn * BM + wc * 32 + 8 * fq;
; #pragma unroll
;         for (int bj = 0; bj < 2; ++bj) {
;             const int c = col0 + bj * HALF;
;             f32x4 cs0 = {1.f, 1.f, 1.f, 1.f}, cs1 = {1.f, 1.f, 1.f, 1.f};
;             if (e.mode == 0 && e.colscale) { cs0 = *(const f32x4*)(e.colscale + c); cs1 = *(const f32x4*)(e.colscale + c + 4); }
; #pragma unroll
;             for (int ai = 0; ai < 2; ++ai)
; #pragma unroll
;                 for (int m = 0; m < 4; ++m) {
;                     const int row = row0 + ai * HALF + m * 16;
;                     f32x4 v0 = acc[ai][bj][m][0], v1 = acc[ai][bj][m][1];
;                     if (e.mode == 1) {
; #pragma unroll
;                         for (int j = 0; j < 4; ++j) { const float a = fmaxf(v0[j], 0.f), b = fmaxf(v1[j], 0.f); v0[j] = a * a; v1[j] = b * b; }
;                     } else { v0 *= cs0; v1 *= cs1; }
;                     bf16_t* rowp = (u.ks < 0 ? e.O + (size_t)row * e.ldo : e.Opart + ((size_t)u.ks * MCTX + (row - MLAT)) * 1024) + c;
;                     if (e.mode == 1)
;                         rowp = (bf16_t*)((char*)e.O + ((size_t)(u.pm * 64 + u.pn * 4 + bj * 2 + (wc >> 1))) * 32768 + ai * 16384 + (((wr * 4 + m) * 2 + (wc & 1)) * 1024) + (fr * 4 + fq) * 16);
;                     u32x4 w; w.x = cvt_pk_bf16(v0[0], v0[1]); w.y = cvt_pk_bf16(v0[2], v0[3]); w.z = cvt_pk_bf16(v1[0], v1[1]); w.w = cvt_pk_bf16(v1[2], v1[3]);
;                     *(u32x4*)rowp = w;
.Lep0_cs:
	v_readlane_b32 s20, v255, 5
	v_readlane_b32 s21, v255, 6
	s_lshl_b32 s19, s85, 10
	s_add_u32 s20, s20, s19
	s_addc_u32 s21, s21, 0
	v_lshlrev_b32_e32 v217, 2, v218
	s_nop 1
	global_load_dwordx4 v[220:223], v217, s[20:21]
	global_load_dwordx4 v[224:227], v217, s[20:21] offset:16
	global_load_dwordx4 v[228:231], v217, s[20:21] offset:512
	global_load_dwordx4 v[232:235], v217, s[20:21] offset:528
	s_waitcnt vmcnt(0)
	s_mov_b64 s[98:99], s[100:101]
	v_pk_mul_f32 v[236:237], v[128:129], v[220:221]
	v_pk_mul_f32 v[238:239], v[130:131], v[222:223]
	v_pk_mul_f32 v[240:241], v[124:125], v[224:225]
	v_pk_mul_f32 v[242:243], v[126:127], v[226:227]
	v_cvt_pk_bf16_f32 v244, v236, v237
	v_cvt_pk_bf16_f32 v245, v238, v239
	v_cvt_pk_bf16_f32 v246, v240, v241
	v_cvt_pk_bf16_f32 v247, v242, v243
	global_store_dwordx4 v216, v[244:247], s[98:99]
	s_mul_i32 s16, s17, 1
	s_add_u32 s98, s100, s16
	s_addc_u32 s99, s101, 0
	v_pk_mul_f32 v[236:237], v[120:121], v[220:221]
	v_pk_mul_f32 v[238:239], v[122:123], v[222:223]
	v_pk_mul_f32 v[240:241], v[116:117], v[224:225]
	v_pk_mul_f32 v[242:243], v[118:119], v[226:227]
	v_cvt_pk_bf16_f32 v248, v236, v237
	v_cvt_pk_bf16_f32 v249, v238, v239
	v_cvt_pk_bf16_f32 v250, v240, v241
	v_cvt_pk_bf16_f32 v251, v242, v243
	global_store_dwordx4 v216, v[248:251], s[98:99]
	s_mul_i32 s16, s17, 2
	s_add_u32 s98, s100, s16
	s_addc_u32 s99, s101, 0
	v_pk_mul_f32 v[236:237], v[112:113], v[220:221]
	v_pk_mul_f32 v[238:239], v[114:115], v[222:223]
	v_pk_mul_f32 v[240:241], v[108:109], v[224:225]
	v_pk_mul_f32 v[242:243], v[110:111], v[226:227]
	v_cvt_pk_bf16_f32 v204, v236, v237
	v_cvt_pk_bf16_f32 v205, v238, v239
	v_cvt_pk_bf16_f32 v206, v240, v241
	v_cvt_pk_bf16_f32 v207, v242, v243
	global_store_dwordx4 v216, v[204:207], s[98:99]
	s_mul_i32 s16, s17, 3
	s_add_u32 s98, s100, s16
	s_addc_u32 s99, s101, 0
	v_pk_mul_f32 v[236:237], v[104:105], v[220:221]
	v_pk_mul_f32 v[238:239], v[106:107], v[222:223]
	v_pk_mul_f32 v[240:241], v[100:101], v[224:225]
	v_pk_mul_f32 v[242:243], v[102:103], v[226:227]
	v_cvt_pk_bf16_f32 v132, v236, v237
	v_cvt_pk_bf16_f32 v133, v238, v239
	v_cvt_pk_bf16_f32 v134, v240, v241
	v_cvt_pk_bf16_f32 v135, v242, v243
	global_store_dwordx4 v216, v[132:135], s[98:99]
	s_mul_i32 s16, s17, 8
	s_add_u32 s98, s100, s16
	s_addc_u32 s99, s101, 0
	v_pk_mul_f32 v[236:237], v[60:61], v[220:221]
	v_pk_mul_f32 v[238:239], v[62:63], v[222:223]
	v_pk_mul_f32 v[240:241], v[56:57], v[224:225]
	v_pk_mul_f32 v[242:243], v[58:59], v[226:227]
	v_cvt_pk_bf16_f32 v244, v236, v237
	v_cvt_pk_bf16_f32 v245, v238, v239
	v_cvt_pk_bf16_f32 v246, v240, v241
	v_cvt_pk_bf16_f32 v247, v242, v243
	global_store_dwordx4 v216, v[244:247], s[98:99]
	s_mul_i32 s16, s17, 9
	s_add_u32 s98, s100, s16
	s_addc_u32 s99, s101, 0
	v_pk_mul_f32 v[236:237], v[52:53], v[220:221]
	v_pk_mul_f32 v[238:239], v[54:55], v[222:223]
	v_pk_mul_f32 v[240:241], v[48:49], v[224:225]
	v_pk_mul_f32 v[242:243], v[50:51], v[226:227]
	v_cvt_pk_bf16_f32 v248, v236, v237
	v_cvt_pk_bf16_f32 v249, v238, v239
	v_cvt_pk_bf16_f32 v250, v240, v241
	v_cvt_pk_bf16_f32 v251, v242, v243
	global_store_dwordx4 v216, v[248:251], s[98:99]
	s_mul_i32 s16, s17, 10
	s_add_u32 s98, s100, s16
	s_addc_u32 s99, s101, 0
	v_pk_mul_f32 v[236:237], v[44:45], v[220:221]
	v_pk_mul_f32 v[238:239], v[46:47], v[222:223]
	v_pk_mul_f32 v[240:241], v[40:41], v[224:225]
	v_pk_mul_f32 v[242:243], v[42:43], v[226:227]
	v_cvt_pk_bf16_f32 v204, v236, v237
	v_cvt_pk_bf16_f32 v205, v238, v239
	v_cvt_pk_bf16_f32 v206, v240, v241
	v_cvt_pk_bf16_f32 v207, v242, v243
	global_store_dwordx4 v216, v[204:207], s[98:99]
	s_mul_i32 s16, s17, 11
	s_add_u32 s98, s100, s16
	s_addc_u32 s99, s101, 0
	v_pk_mul_f32 v[236:237], v[36:37], v[220:221]
	v_pk_mul_f32 v[238:239], v[38:39], v[222:223]
	v_pk_mul_f32 v[240:241], v[32:33], v[224:225]
	v_pk_mul_f32 v[242:243], v[34:35], v[226:227]
	v_cvt_pk_bf16_f32 v132, v236, v237
	v_cvt_pk_bf16_f32 v133, v238, v239
	v_cvt_pk_bf16_f32 v134, v240, v241
	v_cvt_pk_bf16_f32 v135, v242, v243
	global_store_dwordx4 v216, v[132:135], s[98:99]
	s_mov_b64 s[98:99], s[100:101]
	v_pk_mul_f32 v[236:237], v[92:93], v[228:229]
	v_pk_mul_f32 v[238:239], v[94:95], v[230:231]
	v_pk_mul_f32 v[240:241], v[88:89], v[232:233]
	v_pk_mul_f32 v[242:243], v[90:91], v[234:235]
	v_cvt_pk_bf16_f32 v244, v236, v237
	v_cvt_pk_bf16_f32 v245, v238, v239
	v_cvt_pk_bf16_f32 v246, v240, v241
	v_cvt_pk_bf16_f32 v247, v242, v243
	global_store_dwordx4 v216, v[244:247], s[98:99] offset:256
	s_mul_i32 s16, s17, 1
	s_add_u32 s98, s100, s16
	s_addc_u32 s99, s101, 0
	v_pk_mul_f32 v[236:237], v[84:85], v[228:229]
	v_pk_mul_f32 v[238:239], v[86:87], v[230:231]
	v_pk_mul_f32 v[240:241], v[80:81], v[232:233]
	v_pk_mul_f32 v[242:243], v[82:83], v[234:235]
	v_cvt_pk_bf16_f32 v248, v236, v237
	v_cvt_pk_bf16_f32 v249, v238, v239
	v_cvt_pk_bf16_f32 v250, v240, v241
	v_cvt_pk_bf16_f32 v251, v242, v243
	global_store_dwordx4 v216, v[248:251], s[98:99] offset:256
	s_mul_i32 s16, s17, 2
	s_add_u32 s98, s100, s16
	s_addc_u32 s99, s101, 0
	v_pk_mul_f32 v[236:237], v[76:77], v[228:229]
	v_pk_mul_f32 v[238:239], v[78:79], v[230:231]
	v_pk_mul_f32 v[240:241], v[72:73], v[232:233]
	v_pk_mul_f32 v[242:243], v[74:75], v[234:235]
	v_cvt_pk_bf16_f32 v204, v236, v237
	v_cvt_pk_bf16_f32 v205, v238, v239
	v_cvt_pk_bf16_f32 v206, v240, v241
	v_cvt_pk_bf16_f32 v207, v242, v243
	global_store_dwordx4 v216, v[204:207], s[98:99] offset:256
	s_mul_i32 s16, s17, 3
	s_add_u32 s98, s100, s16
	s_addc_u32 s99, s101, 0
	v_pk_mul_f32 v[236:237], v[68:69], v[228:229]
	v_pk_mul_f32 v[238:239], v[70:71], v[230:231]
	v_pk_mul_f32 v[240:241], v[64:65], v[232:233]
; __device__ __forceinline__ void epi_store(const f32x4 (&acc)[2][2][4][2], const Unit& u, int wr, int wc, int fr, int fq, const EpiP& e) {
;     ...
;                     if (e.mode == 1) {
; #pragma unroll
;                         for (int j = 0; j < 4; ++j) { const float a = fmaxf(v0[j], 0.f), b = fmaxf(v1[j], 0.f); v0[j] = a * a; v1[j] = b * b; }
;                     } else { v0 *= cs0; v1 *= cs1; }
;                     bf16_t* rowp = (u.ks < 0 ? e.O + (size_t)row * e.ldo : e.Opart + ((size_t)u.ks * MCTX + (row - MLAT)) * 1024) + c;
;                     if (e.mode == 1)
;                         rowp = (bf16_t*)((char*)e.O + ((size_t)(u.pm * 64 + u.pn * 4 + bj * 2 + (wc >> 1))) * 32768 + ai * 16384 + (((wr * 4 + m) * 2 + (wc & 1)) * 1024) + (fr * 4 + fq) * 16);
	v_pk_mul_f32 v[242:243], v[66:67], v[234:235]
	v_cvt_pk_bf16_f32 v132, v236, v237
	v_cvt_pk_bf16_f32 v133, v238, v239
	v_cvt_pk_bf16_f32 v134, v240, v241
	v_cvt_pk_bf16_f32 v135, v242, v243
	global_store_dwordx4 v216, v[132:135], s[98:99] offset:256
	s_mul_i32 s16, s17, 8
	s_add_u32 s98, s100, s16
	s_addc_u32 s99, s101, 0
	v_pk_mul_f32 v[236:237], v[28:29], v[228:229]
	v_pk_mul_f32 v[238:239], v[30:31], v[230:231]
	v_pk_mul_f32 v[240:241], v[24:25], v[232:233]
	v_pk_mul_f32 v[242:243], v[26:27], v[234:235]
	v_cvt_pk_bf16_f32 v244, v236, v237
	v_cvt_pk_bf16_f32 v245, v238, v239
	v_cvt_pk_bf16_f32 v246, v240, v241
	v_cvt_pk_bf16_f32 v247, v242, v243
	global_store_dwordx4 v216, v[244:247], s[98:99] offset:256
	s_mul_i32 s16, s17, 9
	s_add_u32 s98, s100, s16
	s_addc_u32 s99, s101, 0
	v_pk_mul_f32 v[236:237], v[20:21], v[228:229]
	v_pk_mul_f32 v[238:239], v[22:23], v[230:231]
	v_pk_mul_f32 v[240:241], v[16:17], v[232:233]
	v_pk_mul_f32 v[242:243], v[18:19], v[234:235]
	v_cvt_pk_bf16_f32 v248, v236, v237
	v_cvt_pk_bf16_f32 v249, v238, v239
	v_cvt_pk_bf16_f32 v250, v240, v241
	v_cvt_pk_bf16_f32 v251, v242, v243
	global_store_dwordx4 v216, v[248:251], s[98:99] offset:256
	s_mul_i32 s16, s17, 10
	s_add_u32 s98, s100, s16
	s_addc_u32 s99, s101, 0
	v_pk_mul_f32 v[236:237], v[12:13], v[228:229]
	v_pk_mul_f32 v[238:239], v[14:15], v[230:231]
	v_pk_mul_f32 v[240:241], v[8:9], v[232:233]
	v_pk_mul_f32 v[242:243], v[10:11], v[234:235]
	v_cvt_pk_bf16_f32 v204, v236, v237
	v_cvt_pk_bf16_f32 v205, v238, v239
	v_cvt_pk_bf16_f32 v206, v240, v241
	v_cvt_pk_bf16_f32 v207, v242, v243
	global_store_dwordx4 v216, v[204:207], s[98:99] offset:256
	s_mul_i32 s16, s17, 11
	s_add_u32 s98, s100, s16
	s_addc_u32 s99, s101, 0
	v_pk_mul_f32 v[236:237], v[4:5], v[228:229]
	v_pk_mul_f32 v[238:239], v[6:7], v[230:231]
	v_pk_mul_f32 v[240:241], v[0:1], v[232:233]
	v_pk_mul_f32 v[242:243], v[2:3], v[234:235]
	v_cvt_pk_bf16_f32 v132, v236, v237
	v_cvt_pk_bf16_f32 v133, v238, v239
	v_cvt_pk_bf16_f32 v134, v240, v241
	v_cvt_pk_bf16_f32 v135, v242, v243
	global_store_dwordx4 v216, v[132:135], s[98:99] offset:256
	s_branch .Lep_done
.Lep1_setup:
	s_lshl_b32 s16, s87, 6
	s_lshl_b32 s17, s85, 2
	s_add_i32 s16, s16, s17
	s_lshl_b32 s16, s16, 15
	s_add_u32 s100, s74, s16
	s_addc_u32 s101, s75, 0
	v_lshl_or_b32 v217, v217, 2, v219
	v_lshlrev_b32_e32 v217, 4, v217
	v_lshl_or_b32 v217, v218, 13, v217
	v_bfe_u32 v218, v159, 6, 1
	v_lshl_or_b32 v217, v218, 10, v217
	v_bfe_u32 v218, v159, 7, 1
	v_lshl_or_b32 v216, v218, 15, v217
	s_mov_b64 s[98:99], s[100:101]
	v_max_f32_e32 v220, 0, v128
	v_max_f32_e32 v221, 0, v129
	v_max_f32_e32 v222, 0, v130
	v_max_f32_e32 v223, 0, v131
	v_max_f32_e32 v224, 0, v124
	v_max_f32_e32 v225, 0, v125
	v_max_f32_e32 v226, 0, v126
	v_max_f32_e32 v227, 0, v127
	v_pk_mul_f32 v[220:221], v[220:221], v[220:221]
	v_pk_mul_f32 v[222:223], v[222:223], v[222:223]
	v_pk_mul_f32 v[224:225], v[224:225], v[224:225]
	v_pk_mul_f32 v[226:227], v[226:227], v[226:227]
	v_cvt_pk_bf16_f32 v204, v220, v221
	v_cvt_pk_bf16_f32 v205, v222, v223
	v_cvt_pk_bf16_f32 v206, v224, v225
	v_cvt_pk_bf16_f32 v207, v226, v227
	global_store_dwordx4 v216, v[204:207], s[98:99]
	s_add_u32 s98, s100, 0x800
	s_addc_u32 s99, s101, 0
	v_max_f32_e32 v228, 0, v120
	v_max_f32_e32 v229, 0, v121
	v_max_f32_e32 v230, 0, v122
	v_max_f32_e32 v231, 0, v123
	v_max_f32_e32 v232, 0, v116
	v_max_f32_e32 v233, 0, v117
	v_max_f32_e32 v234, 0, v118
	v_max_f32_e32 v235, 0, v119
	v_pk_mul_f32 v[228:229], v[228:229], v[228:229]
	v_pk_mul_f32 v[230:231], v[230:231], v[230:231]
	v_pk_mul_f32 v[232:233], v[232:233], v[232:233]
	v_pk_mul_f32 v[234:235], v[234:235], v[234:235]
	v_cvt_pk_bf16_f32 v132, v228, v229
	v_cvt_pk_bf16_f32 v133, v230, v231
	v_cvt_pk_bf16_f32 v134, v232, v233
	v_cvt_pk_bf16_f32 v135, v234, v235
	global_store_dwordx4 v216, v[132:135], s[98:99]
	s_add_u32 s98, s100, 0x1000
	s_addc_u32 s99, s101, 0
	v_max_f32_e32 v220, 0, v112
	v_max_f32_e32 v221, 0, v113
	v_max_f32_e32 v222, 0, v114
	v_max_f32_e32 v223, 0, v115
	v_max_f32_e32 v224, 0, v108
	v_max_f32_e32 v225, 0, v109
	v_max_f32_e32 v226, 0, v110
	v_max_f32_e32 v227, 0, v111
	v_pk_mul_f32 v[220:221], v[220:221], v[220:221]
	v_pk_mul_f32 v[222:223], v[222:223], v[222:223]
	v_pk_mul_f32 v[224:225], v[224:225], v[224:225]
	v_pk_mul_f32 v[226:227], v[226:227], v[226:227]
	v_cvt_pk_bf16_f32 v136, v220, v221
	v_cvt_pk_bf16_f32 v137, v222, v223
	v_cvt_pk_bf16_f32 v138, v224, v225
	v_cvt_pk_bf16_f32 v139, v226, v227
	global_store_dwordx4 v216, v[136:139], s[98:99]
	s_add_u32 s98, s100, 0x1800
	s_addc_u32 s99, s101, 0
	v_max_f32_e32 v228, 0, v104
	v_max_f32_e32 v229, 0, v105
	v_max_f32_e32 v230, 0, v106
	v_max_f32_e32 v231, 0, v107
	v_max_f32_e32 v232, 0, v100
	v_max_f32_e32 v233, 0, v101
	v_max_f32_e32 v234, 0, v102
	v_max_f32_e32 v235, 0, v103
	v_pk_mul_f32 v[228:229], v[228:229], v[228:229]
	v_pk_mul_f32 v[230:231], v[230:231], v[230:231]
	v_pk_mul_f32 v[232:233], v[232:233], v[232:233]
	v_pk_mul_f32 v[234:235], v[234:235], v[234:235]
	v_cvt_pk_bf16_f32 v160, v228, v229
	v_cvt_pk_bf16_f32 v161, v230, v231
	v_cvt_pk_bf16_f32 v162, v232, v233
	v_cvt_pk_bf16_f32 v163, v234, v235
	global_store_dwordx4 v216, v[160:163], s[98:99]
	s_add_u32 s98, s100, 0x4000
	s_addc_u32 s99, s101, 0
	v_max_f32_e32 v220, 0, v60
	v_max_f32_e32 v221, 0, v61
	v_max_f32_e32 v222, 0, v62
	v_max_f32_e32 v223, 0, v63
	v_max_f32_e32 v224, 0, v56
	v_max_f32_e32 v225, 0, v57
	v_max_f32_e32 v226, 0, v58
	v_max_f32_e32 v227, 0, v59
	v_pk_mul_f32 v[220:221], v[220:221], v[220:221]
	v_pk_mul_f32 v[222:223], v[222:223], v[222:223]
	v_pk_mul_f32 v[224:225], v[224:225], v[224:225]
; __device__ __forceinline__ unsigned cvt_pk_bf16(float lo, float hi) { unsigned r; asm volatile("v_cvt_pk_bf16_f32 %0, %1, %2" : "=v"(r) : "v"(lo), "v"(hi)); return r; }
; __device__ __forceinline__ void epi_store(const f32x4 (&acc)[2][2][4][2], const Unit& u, int wr, int wc, int fr, int fq, const EpiP& e) {
;     ...
;                     if (e.mode == 1) {
; #pragma unroll
;                         for (int j = 0; j < 4; ++j) { const float a = fmaxf(v0[j], 0.f), b = fmaxf(v1[j], 0.f); v0[j] = a * a; v1[j] = b * b; }
;                     } else { v0 *= cs0; v1 *= cs1; }
;                     bf16_t* rowp = (u.ks < 0 ? e.O + (size_t)row * e.ldo : e.Opart + ((size_t)u.ks * MCTX + (row - MLAT)) * 1024) + c;
;                     if (e.mode == 1)
;                         rowp = (bf16_t*)((char*)e.O + ((size_t)(u.pm * 64 + u.pn * 4 + bj * 2 + (wc >> 1))) * 32768 + ai * 16384 + (((wr * 4 + m) * 2 + (wc & 1)) * 1024) + (fr * 4 + fq) * 16);
;                     u32x4 w; w.x = cvt_pk_bf16(v0[0], v0[1]); w.y = cvt_pk_bf16(v0[2], v0[3]); w.z = cvt_pk_bf16(v1[0], v1[1]); w.w = cvt_pk_bf16(v1[2], v1[3]);
;                     *(u32x4*)rowp = w;
	v_pk_mul_f32 v[226:227], v[226:227], v[226:227]
	v_cvt_pk_bf16_f32 v164, v220, v221
	v_cvt_pk_bf16_f32 v165, v222, v223
	v_cvt_pk_bf16_f32 v166, v224, v225
	v_cvt_pk_bf16_f32 v167, v226, v227
	global_store_dwordx4 v216, v[164:167], s[98:99]
	s_add_u32 s98, s100, 0x4800
	s_addc_u32 s99, s101, 0
	v_max_f32_e32 v228, 0, v52
	v_max_f32_e32 v229, 0, v53
	v_max_f32_e32 v230, 0, v54
	v_max_f32_e32 v231, 0, v55
	v_max_f32_e32 v232, 0, v48
	v_max_f32_e32 v233, 0, v49
	v_max_f32_e32 v234, 0, v50
	v_max_f32_e32 v235, 0, v51
	v_pk_mul_f32 v[228:229], v[228:229], v[228:229]
	v_pk_mul_f32 v[230:231], v[230:231], v[230:231]
	v_pk_mul_f32 v[232:233], v[232:233], v[232:233]
	v_pk_mul_f32 v[234:235], v[234:235], v[234:235]
	v_cvt_pk_bf16_f32 v168, v228, v229
	v_cvt_pk_bf16_f32 v169, v230, v231
	v_cvt_pk_bf16_f32 v170, v232, v233
	v_cvt_pk_bf16_f32 v171, v234, v235
	global_store_dwordx4 v216, v[168:171], s[98:99]
	s_add_u32 s98, s100, 0x5000
	s_addc_u32 s99, s101, 0
	v_max_f32_e32 v220, 0, v44
	v_max_f32_e32 v221, 0, v45
	v_max_f32_e32 v222, 0, v46
	v_max_f32_e32 v223, 0, v47
	v_max_f32_e32 v224, 0, v40
	v_max_f32_e32 v225, 0, v41
	v_max_f32_e32 v226, 0, v42
	v_max_f32_e32 v227, 0, v43
	v_pk_mul_f32 v[220:221], v[220:221], v[220:221]
	v_pk_mul_f32 v[222:223], v[222:223], v[222:223]
	v_pk_mul_f32 v[224:225], v[224:225], v[224:225]
	v_pk_mul_f32 v[226:227], v[226:227], v[226:227]
	v_cvt_pk_bf16_f32 v172, v220, v221
	v_cvt_pk_bf16_f32 v173, v222, v223
	v_cvt_pk_bf16_f32 v174, v224, v225
	v_cvt_pk_bf16_f32 v175, v226, v227
	global_store_dwordx4 v216, v[172:175], s[98:99]
	s_add_u32 s98, s100, 0x5800
	s_addc_u32 s99, s101, 0
	v_max_f32_e32 v228, 0, v36
	v_max_f32_e32 v229, 0, v37
	v_max_f32_e32 v230, 0, v38
	v_max_f32_e32 v231, 0, v39
	v_max_f32_e32 v232, 0, v32
	v_max_f32_e32 v233, 0, v33
	v_max_f32_e32 v234, 0, v34
	v_max_f32_e32 v235, 0, v35
	v_pk_mul_f32 v[228:229], v[228:229], v[228:229]
	v_pk_mul_f32 v[230:231], v[230:231], v[230:231]
	v_pk_mul_f32 v[232:233], v[232:233], v[232:233]
	v_pk_mul_f32 v[234:235], v[234:235], v[234:235]
	v_cvt_pk_bf16_f32 v248, v228, v229
	v_cvt_pk_bf16_f32 v249, v230, v231
	v_cvt_pk_bf16_f32 v250, v232, v233
	v_cvt_pk_bf16_f32 v251, v234, v235
	global_store_dwordx4 v216, v[248:251], s[98:99]
	s_add_u32 s98, s100, 0x10000
	s_addc_u32 s99, s101, 0
	v_max_f32_e32 v220, 0, v92
	v_max_f32_e32 v221, 0, v93
	v_max_f32_e32 v222, 0, v94
	v_max_f32_e32 v223, 0, v95
	v_max_f32_e32 v224, 0, v88
	v_max_f32_e32 v225, 0, v89
	v_max_f32_e32 v226, 0, v90
	v_max_f32_e32 v227, 0, v91
	v_pk_mul_f32 v[220:221], v[220:221], v[220:221]
	v_pk_mul_f32 v[222:223], v[222:223], v[222:223]
	v_pk_mul_f32 v[224:225], v[224:225], v[224:225]
	v_pk_mul_f32 v[226:227], v[226:227], v[226:227]
	v_cvt_pk_bf16_f32 v204, v220, v221
	v_cvt_pk_bf16_f32 v205, v222, v223
	v_cvt_pk_bf16_f32 v206, v224, v225
	v_cvt_pk_bf16_f32 v207, v226, v227
	global_store_dwordx4 v216, v[204:207], s[98:99]
	s_add_u32 s98, s100, 0x10800
	s_addc_u32 s99, s101, 0
	v_max_f32_e32 v228, 0, v84
	v_max_f32_e32 v229, 0, v85
	v_max_f32_e32 v230, 0, v86
	v_max_f32_e32 v231, 0, v87
	v_max_f32_e32 v232, 0, v80
	v_max_f32_e32 v233, 0, v81
	v_max_f32_e32 v234, 0, v82
	v_max_f32_e32 v235, 0, v83
	v_pk_mul_f32 v[228:229], v[228:229], v[228:229]
	v_pk_mul_f32 v[230:231], v[230:231], v[230:231]
	v_pk_mul_f32 v[232:233], v[232:233], v[232:233]
	v_pk_mul_f32 v[234:235], v[234:235], v[234:235]
	v_cvt_pk_bf16_f32 v132, v228, v229
	v_cvt_pk_bf16_f32 v133, v230, v231
	v_cvt_pk_bf16_f32 v134, v232, v233
	v_cvt_pk_bf16_f32 v135, v234, v235
	global_store_dwordx4 v216, v[132:135], s[98:99]
	s_add_u32 s98, s100, 0x11000
	s_addc_u32 s99, s101, 0
	v_max_f32_e32 v220, 0, v76
	v_max_f32_e32 v221, 0, v77
	v_max_f32_e32 v222, 0, v78
	v_max_f32_e32 v223, 0, v79
	v_max_f32_e32 v224, 0, v72
	v_max_f32_e32 v225, 0, v73
	v_max_f32_e32 v226, 0, v74
	v_max_f32_e32 v227, 0, v75
	v_pk_mul_f32 v[220:221], v[220:221], v[220:221]
; __device__ __forceinline__ unsigned cvt_pk_bf16(float lo, float hi) { unsigned r; asm volatile("v_cvt_pk_bf16_f32 %0, %1, %2" : "=v"(r) : "v"(lo), "v"(hi)); return r; }
; #define PG8_BAR __builtin_amdgcn_s_barrier()
; __device__ __forceinline__ void epi_store(const f32x4 (&acc)[2][2][4][2], const Unit& u, int wr, int wc, int fr, int fq, const EpiP& e) {
;     ...
;                     if (e.mode == 1) {
; #pragma unroll
;                         for (int j = 0; j < 4; ++j) { const float a = fmaxf(v0[j], 0.f), b = fmaxf(v1[j], 0.f); v0[j] = a * a; v1[j] = b * b; }
;                     } else { v0 *= cs0; v1 *= cs1; }
;                     bf16_t* rowp = (u.ks < 0 ? e.O + (size_t)row * e.ldo : e.Opart + ((size_t)u.ks * MCTX + (row - MLAT)) * 1024) + c;
;                     if (e.mode == 1)
;                         rowp = (bf16_t*)((char*)e.O + ((size_t)(u.pm * 64 + u.pn * 4 + bj * 2 + (wc >> 1))) * 32768 + ai * 16384 + (((wr * 4 + m) * 2 + (wc & 1)) * 1024) + (fr * 4 + fq) * 16);
;                     u32x4 w; w.x = cvt_pk_bf16(v0[0], v0[1]); w.y = cvt_pk_bf16(v0[2], v0[3]); w.z = cvt_pk_bf16(v1[0], v1[1]); w.w = cvt_pk_bf16(v1[2], v1[3]);
;                     *(u32x4*)rowp = w;
; __device__ __forceinline__ void gemm_phase(LAS unsigned char* lds, const GemmP g, const EpiP e) {
;     ...
;         if (!has_next) break;
; #pragma unroll
;         for (int a = 0; a < 2; ++a)
; #pragma unroll
;             for (int b = 0; b < 2; ++b)
; #pragma unroll
;                 for (int m = 0; m < 4; ++m)
; #pragma unroll
;                     for (int n = 0; n < 2; ++n) acc[a][b][m][n] = (f32x4){0.f, 0.f, 0.f, 0.f};
;         cur = nxt; cA = nA; cB = nB; ++ui;
;         if (wr == 1) PG8_BAR;
	v_pk_mul_f32 v[222:223], v[222:223], v[222:223]
	v_pk_mul_f32 v[224:225], v[224:225], v[224:225]
	v_pk_mul_f32 v[226:227], v[226:227], v[226:227]
	v_cvt_pk_bf16_f32 v136, v220, v221
	v_cvt_pk_bf16_f32 v137, v222, v223
	v_cvt_pk_bf16_f32 v138, v224, v225
	v_cvt_pk_bf16_f32 v139, v226, v227
	global_store_dwordx4 v216, v[136:139], s[98:99]
	s_add_u32 s98, s100, 0x11800
	s_addc_u32 s99, s101, 0
	v_max_f32_e32 v228, 0, v68
	v_max_f32_e32 v229, 0, v69
	v_max_f32_e32 v230, 0, v70
	v_max_f32_e32 v231, 0, v71
	v_max_f32_e32 v232, 0, v64
	v_max_f32_e32 v233, 0, v65
	v_max_f32_e32 v234, 0, v66
	v_max_f32_e32 v235, 0, v67
	v_pk_mul_f32 v[228:229], v[228:229], v[228:229]
	v_pk_mul_f32 v[230:231], v[230:231], v[230:231]
	v_pk_mul_f32 v[232:233], v[232:233], v[232:233]
	v_pk_mul_f32 v[234:235], v[234:235], v[234:235]
	v_cvt_pk_bf16_f32 v160, v228, v229
	v_cvt_pk_bf16_f32 v161, v230, v231
	v_cvt_pk_bf16_f32 v162, v232, v233
	v_cvt_pk_bf16_f32 v163, v234, v235
	global_store_dwordx4 v216, v[160:163], s[98:99]
	s_add_u32 s98, s100, 0x14000
	s_addc_u32 s99, s101, 0
	v_max_f32_e32 v220, 0, v28
	v_max_f32_e32 v221, 0, v29
	v_max_f32_e32 v222, 0, v30
	v_max_f32_e32 v223, 0, v31
	v_max_f32_e32 v224, 0, v24
	v_max_f32_e32 v225, 0, v25
	v_max_f32_e32 v226, 0, v26
	v_max_f32_e32 v227, 0, v27
	v_pk_mul_f32 v[220:221], v[220:221], v[220:221]
	v_pk_mul_f32 v[222:223], v[222:223], v[222:223]
	v_pk_mul_f32 v[224:225], v[224:225], v[224:225]
	v_pk_mul_f32 v[226:227], v[226:227], v[226:227]
	v_cvt_pk_bf16_f32 v164, v220, v221
	v_cvt_pk_bf16_f32 v165, v222, v223
	v_cvt_pk_bf16_f32 v166, v224, v225
	v_cvt_pk_bf16_f32 v167, v226, v227
	global_store_dwordx4 v216, v[164:167], s[98:99]
	s_add_u32 s98, s100, 0x14800
	s_addc_u32 s99, s101, 0
	v_max_f32_e32 v228, 0, v20
	v_max_f32_e32 v229, 0, v21
	v_max_f32_e32 v230, 0, v22
	v_max_f32_e32 v231, 0, v23
	v_max_f32_e32 v232, 0, v16
	v_max_f32_e32 v233, 0, v17
	v_max_f32_e32 v234, 0, v18
	v_max_f32_e32 v235, 0, v19
	v_pk_mul_f32 v[228:229], v[228:229], v[228:229]
	v_pk_mul_f32 v[230:231], v[230:231], v[230:231]
	v_pk_mul_f32 v[232:233], v[232:233], v[232:233]
	v_pk_mul_f32 v[234:235], v[234:235], v[234:235]
	v_cvt_pk_bf16_f32 v168, v228, v229
	v_cvt_pk_bf16_f32 v169, v230, v231
	v_cvt_pk_bf16_f32 v170, v232, v233
	v_cvt_pk_bf16_f32 v171, v234, v235
	global_store_dwordx4 v216, v[168:171], s[98:99]
	s_add_u32 s98, s100, 0x15000
	s_addc_u32 s99, s101, 0
	v_max_f32_e32 v220, 0, v12
	v_max_f32_e32 v221, 0, v13
	v_max_f32_e32 v222, 0, v14
	v_max_f32_e32 v223, 0, v15
	v_max_f32_e32 v224, 0, v8
	v_max_f32_e32 v225, 0, v9
	v_max_f32_e32 v226, 0, v10
	v_max_f32_e32 v227, 0, v11
	v_pk_mul_f32 v[220:221], v[220:221], v[220:221]
	v_pk_mul_f32 v[222:223], v[222:223], v[222:223]
	v_pk_mul_f32 v[224:225], v[224:225], v[224:225]
	v_pk_mul_f32 v[226:227], v[226:227], v[226:227]
	v_cvt_pk_bf16_f32 v172, v220, v221
	v_cvt_pk_bf16_f32 v173, v222, v223
	v_cvt_pk_bf16_f32 v174, v224, v225
	v_cvt_pk_bf16_f32 v175, v226, v227
	global_store_dwordx4 v216, v[172:175], s[98:99]
	s_add_u32 s98, s100, 0x15800
	s_addc_u32 s99, s101, 0
	v_max_f32_e32 v228, 0, v4
	v_max_f32_e32 v229, 0, v5
	v_max_f32_e32 v230, 0, v6
	v_max_f32_e32 v231, 0, v7
	v_max_f32_e32 v232, 0, v0
	v_max_f32_e32 v233, 0, v1
	v_max_f32_e32 v234, 0, v2
	v_max_f32_e32 v235, 0, v3
	v_pk_mul_f32 v[228:229], v[228:229], v[228:229]
	v_pk_mul_f32 v[230:231], v[230:231], v[230:231]
	v_pk_mul_f32 v[232:233], v[232:233], v[232:233]
	v_pk_mul_f32 v[234:235], v[234:235], v[234:235]
	v_cvt_pk_bf16_f32 v248, v228, v229
	v_cvt_pk_bf16_f32 v249, v230, v231
	v_cvt_pk_bf16_f32 v250, v232, v233
	v_cvt_pk_bf16_f32 v251, v234, v235
	global_store_dwordx4 v216, v[248:251], s[98:99]
.Lep_done:
	s_and_b64 vcc, exec, s[14:15]
	s_cbranch_vccnz .LBB0_371
.LBB0_574:
	v_readlane_b32 s14, v255, 1
	v_readlane_b32 s15, v255, 2
	s_andn2_b64 vcc, exec, s[14:15]
	s_cbranch_vccnz .LBB0_370
	s_barrier
	s_branch .LBB0_370

; __global__ void __launch_bounds__(NTHREADS, 2) mk_fwd(Params p_arg) {
	.amdhsa_kernel _Z6mk_fwd6Params
		.amdhsa_group_segment_fixed_size 0
		.amdhsa_private_segment_fixed_size 0
		.amdhsa_kernarg_size 472
		.amdhsa_user_sgpr_count 2
		.amdhsa_user_sgpr_dispatch_ptr 0
		.amdhsa_user_sgpr_queue_ptr 0
		.amdhsa_user_sgpr_kernarg_segment_ptr 1
		.amdhsa_user_sgpr_dispatch_id 0
		.amdhsa_user_sgpr_kernarg_preload_length 0
		.amdhsa_user_sgpr_kernarg_preload_offset 0
		.amdhsa_user_sgpr_private_segment_size 0
		.amdhsa_uses_dynamic_stack 0
		.amdhsa_enable_private_segment 0
		.amdhsa_system_sgpr_workgroup_id_x 1
		.amdhsa_system_sgpr_workgroup_id_y 0
		.amdhsa_system_sgpr_workgroup_id_z 0
		.amdhsa_system_sgpr_workgroup_info 0
		.amdhsa_system_vgpr_workitem_id 2
		.amdhsa_next_free_vgpr 256
		.amdhsa_next_free_sgpr 102
		.amdhsa_accum_offset 256
		.amdhsa_reserve_vcc 1
		.amdhsa_float_round_mode_32 0
		.amdhsa_float_round_mode_16_64 0
		.amdhsa_float_denorm_mode_32 3
		.amdhsa_float_denorm_mode_16_64 3
		.amdhsa_dx10_clamp 1
		.amdhsa_ieee_mode 1
		.amdhsa_fp16_overflow 0
		.amdhsa_tg_split 0
		.amdhsa_exception_fp_ieee_invalid_op 0
		.amdhsa_exception_fp_denorm_src 0
		.amdhsa_exception_fp_ieee_div_zero 0
		.amdhsa_exception_fp_ieee_overflow 0
		.amdhsa_exception_fp_ieee_underflow 0
		.amdhsa_exception_fp_ieee_inexact 0
		.amdhsa_exception_int_div_zero 0
	.end_amdhsa_kernel

; __global__ void __launch_bounds__(NTHREADS, 2) mk_fwd(Params p_arg) {
amdhsa.kernels:
  - .agpr_count:     0
    .args:
      - .offset:         0
        .size:           216
        .value_kind:     by_value
      - .offset:         216
        .size:           4
        .value_kind:     hidden_block_count_x
      - .offset:         220
        .size:           4
        .value_kind:     hidden_block_count_y
      - .offset:         224
        .size:           4
        .value_kind:     hidden_block_count_z
      - .offset:         228
        .size:           2
        .value_kind:     hidden_group_size_x
      - .offset:         230
        .size:           2
        .value_kind:     hidden_group_size_y
      - .offset:         232
        .size:           2
        .value_kind:     hidden_group_size_z
      - .offset:         234
        .size:           2
        .value_kind:     hidden_remainder_x
      - .offset:         236
        .size:           2
        .value_kind:     hidden_remainder_y
      - .offset:         238
        .size:           2
        .value_kind:     hidden_remainder_z
      - .offset:         256
        .size:           8
        .value_kind:     hidden_global_offset_x
      - .offset:         264
        .size:           8
        .value_kind:     hidden_global_offset_y
      - .offset:         272
        .size:           8
        .value_kind:     hidden_global_offset_z
      - .offset:         280
        .size:           2
        .value_kind:     hidden_grid_dims
      - .offset:         304
        .size:           8
        .value_kind:     hidden_multigrid_sync_arg
      - .offset:         336
        .size:           4
        .value_kind:     hidden_dynamic_lds_size
    .group_segment_fixed_size: 0
    .kernarg_segment_align: 8
    .kernarg_segment_size: 472
    .language:       OpenCL C
    .language_version:
      - 2
      - 0
    .max_flat_workgroup_size: 512
    .name:           _Z6mk_fwd6Params
    .private_segment_fixed_size: 0
    .sgpr_count:     108
    .sgpr_spill_count: 344
    .symbol:         _Z6mk_fwd6Params.kd
    .uniform_work_group_size: 1
    .uses_dynamic_stack: false
    .vgpr_count:     256
    .vgpr_spill_count: 0
    .wavefront_size: 64
